# prefix phase: 16-byte accesses (8 bf16 per thread per chunk) on waves 0-3, 16 loads in flight, halves the VMEM instruction count
# baseline (speedup 1.0000x reference)
.LBB0_429:
	s_or_b64 exec, exec, s[72:73]
	s_mov_b32 s0, s45
	s_waitcnt lgkmcnt(0)
	s_barrier
	s_add_i32 s0, s0, 0x200e8
	v_mov_b32_e32 v0, s0
	ds_read_b64 v[2:3], v0
	v_readlane_b32 s0, v252, 0
	s_mov_b32 s1, 0x200
	s_waitcnt lgkmcnt(0)
	v_readfirstlane_b32 s2, v2
	v_lshlrev_b32_e32 v2, 1, v200
	v_readfirstlane_b32 s3, v3
	v_lshl_add_u32 v0, s0, 9, v2
	v_cmp_gt_i32_e32 vcc, s1, v2
	s_and_saveexec_b64 s[4:5], vcc
	s_cbranch_execz .LBB0_434
	s_lshl_b32 s0, s0, 9
	v_add_u16_e32 v8, s0, v2
	s_mov_b64 s[6:7], 0
.LBB0_431:
	v_ashrrev_i32_e32 v2, 12, v0
	v_and_b32_e32 v3, 3, v2
	v_cvt_f32_ubyte0_e32 v3, v3
	v_sub_f32_e32 v3, 0xc0a00000, v3
	v_cmp_gt_f32_e32 vcc, s63, v3
	v_mov_b32_e32 v10, 0
	s_mov_b64 s[8:9], 0
	v_cndmask_b32_e32 v4, 0, v207, vcc
	v_add_f32_e32 v3, v3, v4
	v_exp_f32_e32 v3, v3
	v_cndmask_b32_e32 v5, 0, v208, vcc
	v_and_b32_e32 v4, 0xfff, v8
	v_mov_b32_e32 v11, 0
	v_ldexp_f32 v3, v3, v5
	v_sub_f32_e32 v3, 1.0, v3
	v_log_f32_e32 v5, v3
	v_ashrrev_i32_e32 v3, 31, v2
	v_lshlrev_b64 v[2:3], 21, v[2:3]
	v_lshl_or_b32 v2, v4, 3, v2
	v_mul_f32_e32 v5, 0x3f317218, v5
	v_mul_f32_e32 v5, 0x42800000, v5
	v_mul_f32_e32 v5, 0x3fb8aa3b, v5
	v_exp_f32_e32 v9, v5
	v_lshl_add_u64 v[2:3], s[2:3], 0, v[2:3]
	v_mov_b32_e32 v12, 0
	v_mov_b32_e32 v13, 0
	s_mov_b64 s[10:11], 0x4bf0000
	v_lshl_add_u64 v[4:5], v[2:3], 0, s[10:11]
	s_mov_b64 s[10:11], 0x8000
	v_mov_b64_e32 v[6:7], v[4:5]
	v_mov_b32_e32 v88, 0
	v_mov_b32_e32 v89, 0
	v_mov_b32_e32 v90, 0
	v_mov_b32_e32 v91, 0
	v_mov_b32_e32 v92, 0
	v_mov_b32_e32 v93, 0
	v_mov_b32_e32 v94, 0
	v_mov_b32_e32 v95, 0
	global_load_dwordx4 v[20:23], v[4:5], off
	v_lshl_add_u64 v[4:5], v[4:5], 0, s[10:11]
	global_load_dwordx4 v[24:27], v[4:5], off
	v_lshl_add_u64 v[4:5], v[4:5], 0, s[10:11]
	global_load_dwordx4 v[28:31], v[4:5], off
	v_lshl_add_u64 v[4:5], v[4:5], 0, s[10:11]
	global_load_dwordx4 v[32:35], v[4:5], off
	v_lshl_add_u64 v[4:5], v[4:5], 0, s[10:11]
	global_load_dwordx4 v[36:39], v[4:5], off
	v_lshl_add_u64 v[4:5], v[4:5], 0, s[10:11]
	global_load_dwordx4 v[40:43], v[4:5], off
	v_lshl_add_u64 v[4:5], v[4:5], 0, s[10:11]
	global_load_dwordx4 v[44:47], v[4:5], off
	v_lshl_add_u64 v[4:5], v[4:5], 0, s[10:11]
	global_load_dwordx4 v[48:51], v[4:5], off
	v_lshl_add_u64 v[4:5], v[4:5], 0, s[10:11]
	global_load_dwordx4 v[52:55], v[4:5], off
	v_lshl_add_u64 v[4:5], v[4:5], 0, s[10:11]
	global_load_dwordx4 v[56:59], v[4:5], off
	v_lshl_add_u64 v[4:5], v[4:5], 0, s[10:11]
	global_load_dwordx4 v[60:63], v[4:5], off
	v_lshl_add_u64 v[4:5], v[4:5], 0, s[10:11]
	global_load_dwordx4 v[64:67], v[4:5], off
	v_lshl_add_u64 v[4:5], v[4:5], 0, s[10:11]
	global_load_dwordx4 v[68:71], v[4:5], off
	v_lshl_add_u64 v[4:5], v[4:5], 0, s[10:11]
	global_load_dwordx4 v[72:75], v[4:5], off
	v_lshl_add_u64 v[4:5], v[4:5], 0, s[10:11]
	global_load_dwordx4 v[76:79], v[4:5], off
	v_lshl_add_u64 v[4:5], v[4:5], 0, s[10:11]
	global_load_dwordx4 v[80:83], v[4:5], off
	v_lshl_add_u64 v[4:5], v[4:5], 0, s[10:11]
	v_cvt_pk_bf16_f32 v84, v88, v89
	v_cvt_pk_bf16_f32 v85, v90, v91
	v_cvt_pk_bf16_f32 v86, v92, v93
	v_cvt_pk_bf16_f32 v87, v94, v95
	s_waitcnt vmcnt(15)
	global_store_dwordx4 v[6:7], v[84:87], off
	v_lshl_add_u64 v[6:7], v[6:7], 0, s[10:11]
	v_lshlrev_b32_e32 v96, 16, v20
	v_and_b32_e32 v97, 0xffff0000, v20
	v_fma_f32 v88, v9, v88, v96
	v_fma_f32 v89, v9, v89, v97
	v_lshlrev_b32_e32 v96, 16, v21
	v_and_b32_e32 v97, 0xffff0000, v21
	v_fma_f32 v90, v9, v90, v96
	v_fma_f32 v91, v9, v91, v97
	v_lshlrev_b32_e32 v96, 16, v22
	v_and_b32_e32 v97, 0xffff0000, v22
	v_fma_f32 v92, v9, v92, v96
	v_fma_f32 v93, v9, v93, v97
	v_lshlrev_b32_e32 v96, 16, v23
	v_and_b32_e32 v97, 0xffff0000, v23
	v_fma_f32 v94, v9, v94, v96
	v_fma_f32 v95, v9, v95, v97
	global_load_dwordx4 v[20:23], v[4:5], off
	v_lshl_add_u64 v[4:5], v[4:5], 0, s[10:11]
	v_cvt_pk_bf16_f32 v84, v88, v89
	v_cvt_pk_bf16_f32 v85, v90, v91
	v_cvt_pk_bf16_f32 v86, v92, v93
	v_cvt_pk_bf16_f32 v87, v94, v95
	s_waitcnt vmcnt(16)
	global_store_dwordx4 v[6:7], v[84:87], off
	v_lshl_add_u64 v[6:7], v[6:7], 0, s[10:11]
	v_lshlrev_b32_e32 v96, 16, v24
	v_and_b32_e32 v97, 0xffff0000, v24
	v_fma_f32 v88, v9, v88, v96
	v_fma_f32 v89, v9, v89, v97
	v_lshlrev_b32_e32 v96, 16, v25
	v_and_b32_e32 v97, 0xffff0000, v25
	v_fma_f32 v90, v9, v90, v96
	v_fma_f32 v91, v9, v91, v97
	v_lshlrev_b32_e32 v96, 16, v26
	v_and_b32_e32 v97, 0xffff0000, v26
	v_fma_f32 v92, v9, v92, v96
	v_fma_f32 v93, v9, v93, v97
	v_lshlrev_b32_e32 v96, 16, v27
	v_and_b32_e32 v97, 0xffff0000, v27
	v_fma_f32 v94, v9, v94, v96
	v_fma_f32 v95, v9, v95, v97
	global_load_dwordx4 v[24:27], v[4:5], off
	v_lshl_add_u64 v[4:5], v[4:5], 0, s[10:11]
	v_cvt_pk_bf16_f32 v84, v88, v89
	v_cvt_pk_bf16_f32 v85, v90, v91
	v_cvt_pk_bf16_f32 v86, v92, v93
	v_cvt_pk_bf16_f32 v87, v94, v95
	s_waitcnt vmcnt(17)
	global_store_dwordx4 v[6:7], v[84:87], off
	v_lshl_add_u64 v[6:7], v[6:7], 0, s[10:11]
	v_lshlrev_b32_e32 v96, 16, v28
	v_and_b32_e32 v97, 0xffff0000, v28
	v_fma_f32 v88, v9, v88, v96
	v_fma_f32 v89, v9, v89, v97
	v_lshlrev_b32_e32 v96, 16, v29
	v_and_b32_e32 v97, 0xffff0000, v29
	v_fma_f32 v90, v9, v90, v96
	v_fma_f32 v91, v9, v91, v97
	v_lshlrev_b32_e32 v96, 16, v30
	v_and_b32_e32 v97, 0xffff0000, v30
	v_fma_f32 v92, v9, v92, v96
	v_fma_f32 v93, v9, v93, v97
	v_lshlrev_b32_e32 v96, 16, v31
	v_and_b32_e32 v97, 0xffff0000, v31
	v_fma_f32 v94, v9, v94, v96
	v_fma_f32 v95, v9, v95, v97
	global_load_dwordx4 v[28:31], v[4:5], off
	v_lshl_add_u64 v[4:5], v[4:5], 0, s[10:11]
	v_cvt_pk_bf16_f32 v84, v88, v89
	v_cvt_pk_bf16_f32 v85, v90, v91
	v_cvt_pk_bf16_f32 v86, v92, v93
	v_cvt_pk_bf16_f32 v87, v94, v95
	s_waitcnt vmcnt(18)
	global_store_dwordx4 v[6:7], v[84:87], off
	v_lshl_add_u64 v[6:7], v[6:7], 0, s[10:11]
	v_lshlrev_b32_e32 v96, 16, v32
	v_and_b32_e32 v97, 0xffff0000, v32
	v_fma_f32 v88, v9, v88, v96
	v_fma_f32 v89, v9, v89, v97
	v_lshlrev_b32_e32 v96, 16, v33
	v_and_b32_e32 v97, 0xffff0000, v33
	v_fma_f32 v90, v9, v90, v96
	v_fma_f32 v91, v9, v91, v97
	v_lshlrev_b32_e32 v96, 16, v34
	v_and_b32_e32 v97, 0xffff0000, v34
	v_fma_f32 v92, v9, v92, v96
	v_fma_f32 v93, v9, v93, v97
	v_lshlrev_b32_e32 v96, 16, v35
	v_and_b32_e32 v97, 0xffff0000, v35
	v_fma_f32 v94, v9, v94, v96
	v_fma_f32 v95, v9, v95, v97
	global_load_dwordx4 v[32:35], v[4:5], off
	v_lshl_add_u64 v[4:5], v[4:5], 0, s[10:11]
	v_cvt_pk_bf16_f32 v84, v88, v89
	v_cvt_pk_bf16_f32 v85, v90, v91
	v_cvt_pk_bf16_f32 v86, v92, v93
	v_cvt_pk_bf16_f32 v87, v94, v95
	s_waitcnt vmcnt(19)
	global_store_dwordx4 v[6:7], v[84:87], off
	v_lshl_add_u64 v[6:7], v[6:7], 0, s[10:11]
	v_lshlrev_b32_e32 v96, 16, v36
	v_and_b32_e32 v97, 0xffff0000, v36
	v_fma_f32 v88, v9, v88, v96
	v_fma_f32 v89, v9, v89, v97
	v_lshlrev_b32_e32 v96, 16, v37
	v_and_b32_e32 v97, 0xffff0000, v37
	v_fma_f32 v90, v9, v90, v96
	v_fma_f32 v91, v9, v91, v97
	v_lshlrev_b32_e32 v96, 16, v38
	v_and_b32_e32 v97, 0xffff0000, v38
	v_fma_f32 v92, v9, v92, v96
	v_fma_f32 v93, v9, v93, v97
	v_lshlrev_b32_e32 v96, 16, v39
	v_and_b32_e32 v97, 0xffff0000, v39
	v_fma_f32 v94, v9, v94, v96
	v_fma_f32 v95, v9, v95, v97
	global_load_dwordx4 v[36:39], v[4:5], off
	v_lshl_add_u64 v[4:5], v[4:5], 0, s[10:11]
	v_cvt_pk_bf16_f32 v84, v88, v89
	v_cvt_pk_bf16_f32 v85, v90, v91
	v_cvt_pk_bf16_f32 v86, v92, v93
	v_cvt_pk_bf16_f32 v87, v94, v95
	s_waitcnt vmcnt(20)
	global_store_dwordx4 v[6:7], v[84:87], off
	v_lshl_add_u64 v[6:7], v[6:7], 0, s[10:11]
	v_lshlrev_b32_e32 v96, 16, v40
	v_and_b32_e32 v97, 0xffff0000, v40
	v_fma_f32 v88, v9, v88, v96
	v_fma_f32 v89, v9, v89, v97
	v_lshlrev_b32_e32 v96, 16, v41
	v_and_b32_e32 v97, 0xffff0000, v41
	v_fma_f32 v90, v9, v90, v96
	v_fma_f32 v91, v9, v91, v97
	v_lshlrev_b32_e32 v96, 16, v42
	v_and_b32_e32 v97, 0xffff0000, v42
	v_fma_f32 v92, v9, v92, v96
	v_fma_f32 v93, v9, v93, v97
	v_lshlrev_b32_e32 v96, 16, v43
	v_and_b32_e32 v97, 0xffff0000, v43
	v_fma_f32 v94, v9, v94, v96
	v_fma_f32 v95, v9, v95, v97
	global_load_dwordx4 v[40:43], v[4:5], off
	v_lshl_add_u64 v[4:5], v[4:5], 0, s[10:11]
	v_cvt_pk_bf16_f32 v84, v88, v89
	v_cvt_pk_bf16_f32 v85, v90, v91
	v_cvt_pk_bf16_f32 v86, v92, v93
	v_cvt_pk_bf16_f32 v87, v94, v95
	s_waitcnt vmcnt(21)
	global_store_dwordx4 v[6:7], v[84:87], off
	v_lshl_add_u64 v[6:7], v[6:7], 0, s[10:11]
	v_lshlrev_b32_e32 v96, 16, v44
	v_and_b32_e32 v97, 0xffff0000, v44
	v_fma_f32 v88, v9, v88, v96
	v_fma_f32 v89, v9, v89, v97
	v_lshlrev_b32_e32 v96, 16, v45
	v_and_b32_e32 v97, 0xffff0000, v45
	v_fma_f32 v90, v9, v90, v96
	v_fma_f32 v91, v9, v91, v97
	v_lshlrev_b32_e32 v96, 16, v46
	v_and_b32_e32 v97, 0xffff0000, v46
	v_fma_f32 v92, v9, v92, v96
	v_fma_f32 v93, v9, v93, v97
	v_lshlrev_b32_e32 v96, 16, v47
	v_and_b32_e32 v97, 0xffff0000, v47
	v_fma_f32 v94, v9, v94, v96
	v_fma_f32 v95, v9, v95, v97
	global_load_dwordx4 v[44:47], v[4:5], off
	v_lshl_add_u64 v[4:5], v[4:5], 0, s[10:11]
	v_cvt_pk_bf16_f32 v84, v88, v89
	v_cvt_pk_bf16_f32 v85, v90, v91
	v_cvt_pk_bf16_f32 v86, v92, v93
	v_cvt_pk_bf16_f32 v87, v94, v95
	s_waitcnt vmcnt(22)
	global_store_dwordx4 v[6:7], v[84:87], off
	v_lshl_add_u64 v[6:7], v[6:7], 0, s[10:11]
	v_lshlrev_b32_e32 v96, 16, v48
	v_and_b32_e32 v97, 0xffff0000, v48
	v_fma_f32 v88, v9, v88, v96
	v_fma_f32 v89, v9, v89, v97
	v_lshlrev_b32_e32 v96, 16, v49
	v_and_b32_e32 v97, 0xffff0000, v49
	v_fma_f32 v90, v9, v90, v96
	v_fma_f32 v91, v9, v91, v97
	v_lshlrev_b32_e32 v96, 16, v50
	v_and_b32_e32 v97, 0xffff0000, v50
	v_fma_f32 v92, v9, v92, v96
	v_fma_f32 v93, v9, v93, v97
	v_lshlrev_b32_e32 v96, 16, v51
	v_and_b32_e32 v97, 0xffff0000, v51
	v_fma_f32 v94, v9, v94, v96
	v_fma_f32 v95, v9, v95, v97
	global_load_dwordx4 v[48:51], v[4:5], off
	v_lshl_add_u64 v[4:5], v[4:5], 0, s[10:11]
	v_cvt_pk_bf16_f32 v84, v88, v89
	v_cvt_pk_bf16_f32 v85, v90, v91
	v_cvt_pk_bf16_f32 v86, v92, v93
	v_cvt_pk_bf16_f32 v87, v94, v95
	s_waitcnt vmcnt(23)
	global_store_dwordx4 v[6:7], v[84:87], off
	v_lshl_add_u64 v[6:7], v[6:7], 0, s[10:11]
	v_lshlrev_b32_e32 v96, 16, v52
	v_and_b32_e32 v97, 0xffff0000, v52
	v_fma_f32 v88, v9, v88, v96
	v_fma_f32 v89, v9, v89, v97
	v_lshlrev_b32_e32 v96, 16, v53
	v_and_b32_e32 v97, 0xffff0000, v53
	v_fma_f32 v90, v9, v90, v96
	v_fma_f32 v91, v9, v91, v97
	v_lshlrev_b32_e32 v96, 16, v54
	v_and_b32_e32 v97, 0xffff0000, v54
	v_fma_f32 v92, v9, v92, v96
	v_fma_f32 v93, v9, v93, v97
	v_lshlrev_b32_e32 v96, 16, v55
	v_and_b32_e32 v97, 0xffff0000, v55
	v_fma_f32 v94, v9, v94, v96
	v_fma_f32 v95, v9, v95, v97
	global_load_dwordx4 v[52:55], v[4:5], off
	v_lshl_add_u64 v[4:5], v[4:5], 0, s[10:11]
	v_cvt_pk_bf16_f32 v84, v88, v89
	v_cvt_pk_bf16_f32 v85, v90, v91
	v_cvt_pk_bf16_f32 v86, v92, v93
	v_cvt_pk_bf16_f32 v87, v94, v95
	s_waitcnt vmcnt(24)
	global_store_dwordx4 v[6:7], v[84:87], off
	v_lshl_add_u64 v[6:7], v[6:7], 0, s[10:11]
	v_lshlrev_b32_e32 v96, 16, v56
	v_and_b32_e32 v97, 0xffff0000, v56
	v_fma_f32 v88, v9, v88, v96
	v_fma_f32 v89, v9, v89, v97
	v_lshlrev_b32_e32 v96, 16, v57
	v_and_b32_e32 v97, 0xffff0000, v57
	v_fma_f32 v90, v9, v90, v96
	v_fma_f32 v91, v9, v91, v97
	v_lshlrev_b32_e32 v96, 16, v58
	v_and_b32_e32 v97, 0xffff0000, v58
	v_fma_f32 v92, v9, v92, v96
	v_fma_f32 v93, v9, v93, v97
	v_lshlrev_b32_e32 v96, 16, v59
	v_and_b32_e32 v97, 0xffff0000, v59
	v_fma_f32 v94, v9, v94, v96
	v_fma_f32 v95, v9, v95, v97
	global_load_dwordx4 v[56:59], v[4:5], off
	v_lshl_add_u64 v[4:5], v[4:5], 0, s[10:11]
	v_cvt_pk_bf16_f32 v84, v88, v89
	v_cvt_pk_bf16_f32 v85, v90, v91
	v_cvt_pk_bf16_f32 v86, v92, v93
	v_cvt_pk_bf16_f32 v87, v94, v95
	s_waitcnt vmcnt(25)
	global_store_dwordx4 v[6:7], v[84:87], off
	v_lshl_add_u64 v[6:7], v[6:7], 0, s[10:11]
	v_lshlrev_b32_e32 v96, 16, v60
	v_and_b32_e32 v97, 0xffff0000, v60
	v_fma_f32 v88, v9, v88, v96
	v_fma_f32 v89, v9, v89, v97
	v_lshlrev_b32_e32 v96, 16, v61
	v_and_b32_e32 v97, 0xffff0000, v61
	v_fma_f32 v90, v9, v90, v96
	v_fma_f32 v91, v9, v91, v97
	v_lshlrev_b32_e32 v96, 16, v62
	v_and_b32_e32 v97, 0xffff0000, v62
	v_fma_f32 v92, v9, v92, v96
	v_fma_f32 v93, v9, v93, v97
	v_lshlrev_b32_e32 v96, 16, v63
	v_and_b32_e32 v97, 0xffff0000, v63
	v_fma_f32 v94, v9, v94, v96
	v_fma_f32 v95, v9, v95, v97
	global_load_dwordx4 v[60:63], v[4:5], off
	v_lshl_add_u64 v[4:5], v[4:5], 0, s[10:11]
	v_cvt_pk_bf16_f32 v84, v88, v89
	v_cvt_pk_bf16_f32 v85, v90, v91
	v_cvt_pk_bf16_f32 v86, v92, v93
	v_cvt_pk_bf16_f32 v87, v94, v95
	s_waitcnt vmcnt(26)
	global_store_dwordx4 v[6:7], v[84:87], off
	v_lshl_add_u64 v[6:7], v[6:7], 0, s[10:11]
	v_lshlrev_b32_e32 v96, 16, v64
	v_and_b32_e32 v97, 0xffff0000, v64
	v_fma_f32 v88, v9, v88, v96
	v_fma_f32 v89, v9, v89, v97
	v_lshlrev_b32_e32 v96, 16, v65
	v_and_b32_e32 v97, 0xffff0000, v65
	v_fma_f32 v90, v9, v90, v96
	v_fma_f32 v91, v9, v91, v97
	v_lshlrev_b32_e32 v96, 16, v66
	v_and_b32_e32 v97, 0xffff0000, v66
	v_fma_f32 v92, v9, v92, v96
	v_fma_f32 v93, v9, v93, v97
	v_lshlrev_b32_e32 v96, 16, v67
	v_and_b32_e32 v97, 0xffff0000, v67
	v_fma_f32 v94, v9, v94, v96
	v_fma_f32 v95, v9, v95, v97
	global_load_dwordx4 v[64:67], v[4:5], off
	v_lshl_add_u64 v[4:5], v[4:5], 0, s[10:11]
	v_cvt_pk_bf16_f32 v84, v88, v89
	v_cvt_pk_bf16_f32 v85, v90, v91
	v_cvt_pk_bf16_f32 v86, v92, v93
	v_cvt_pk_bf16_f32 v87, v94, v95
	s_waitcnt vmcnt(27)
	global_store_dwordx4 v[6:7], v[84:87], off
	v_lshl_add_u64 v[6:7], v[6:7], 0, s[10:11]
	v_lshlrev_b32_e32 v96, 16, v68
	v_and_b32_e32 v97, 0xffff0000, v68
	v_fma_f32 v88, v9, v88, v96
	v_fma_f32 v89, v9, v89, v97
	v_lshlrev_b32_e32 v96, 16, v69
	v_and_b32_e32 v97, 0xffff0000, v69
	v_fma_f32 v90, v9, v90, v96
	v_fma_f32 v91, v9, v91, v97
	v_lshlrev_b32_e32 v96, 16, v70
	v_and_b32_e32 v97, 0xffff0000, v70
	v_fma_f32 v92, v9, v92, v96
	v_fma_f32 v93, v9, v93, v97
	v_lshlrev_b32_e32 v96, 16, v71
	v_and_b32_e32 v97, 0xffff0000, v71
	v_fma_f32 v94, v9, v94, v96
	v_fma_f32 v95, v9, v95, v97
	global_load_dwordx4 v[68:71], v[4:5], off
	v_lshl_add_u64 v[4:5], v[4:5], 0, s[10:11]
	v_cvt_pk_bf16_f32 v84, v88, v89
	v_cvt_pk_bf16_f32 v85, v90, v91
	v_cvt_pk_bf16_f32 v86, v92, v93
	v_cvt_pk_bf16_f32 v87, v94, v95
	s_waitcnt vmcnt(28)
	global_store_dwordx4 v[6:7], v[84:87], off
	v_lshl_add_u64 v[6:7], v[6:7], 0, s[10:11]
	v_lshlrev_b32_e32 v96, 16, v72
	v_and_b32_e32 v97, 0xffff0000, v72
	v_fma_f32 v88, v9, v88, v96
	v_fma_f32 v89, v9, v89, v97
	v_lshlrev_b32_e32 v96, 16, v73
	v_and_b32_e32 v97, 0xffff0000, v73
	v_fma_f32 v90, v9, v90, v96
	v_fma_f32 v91, v9, v91, v97
	v_lshlrev_b32_e32 v96, 16, v74
	v_and_b32_e32 v97, 0xffff0000, v74
	v_fma_f32 v92, v9, v92, v96
	v_fma_f32 v93, v9, v93, v97
	v_lshlrev_b32_e32 v96, 16, v75
	v_and_b32_e32 v97, 0xffff0000, v75
	v_fma_f32 v94, v9, v94, v96
	v_fma_f32 v95, v9, v95, v97
	global_load_dwordx4 v[72:75], v[4:5], off
	v_lshl_add_u64 v[4:5], v[4:5], 0, s[10:11]
	v_cvt_pk_bf16_f32 v84, v88, v89
	v_cvt_pk_bf16_f32 v85, v90, v91
	v_cvt_pk_bf16_f32 v86, v92, v93
	v_cvt_pk_bf16_f32 v87, v94, v95
	s_waitcnt vmcnt(29)
	global_store_dwordx4 v[6:7], v[84:87], off
	v_lshl_add_u64 v[6:7], v[6:7], 0, s[10:11]
	v_lshlrev_b32_e32 v96, 16, v76
	v_and_b32_e32 v97, 0xffff0000, v76
	v_fma_f32 v88, v9, v88, v96
	v_fma_f32 v89, v9, v89, v97
	v_lshlrev_b32_e32 v96, 16, v77
	v_and_b32_e32 v97, 0xffff0000, v77
	v_fma_f32 v90, v9, v90, v96
	v_fma_f32 v91, v9, v91, v97
	v_lshlrev_b32_e32 v96, 16, v78
	v_and_b32_e32 v97, 0xffff0000, v78
	v_fma_f32 v92, v9, v92, v96
	v_fma_f32 v93, v9, v93, v97
	v_lshlrev_b32_e32 v96, 16, v79
	v_and_b32_e32 v97, 0xffff0000, v79
	v_fma_f32 v94, v9, v94, v96
	v_fma_f32 v95, v9, v95, v97
	global_load_dwordx4 v[76:79], v[4:5], off
	v_lshl_add_u64 v[4:5], v[4:5], 0, s[10:11]
	v_cvt_pk_bf16_f32 v84, v88, v89
	v_cvt_pk_bf16_f32 v85, v90, v91
	v_cvt_pk_bf16_f32 v86, v92, v93
	v_cvt_pk_bf16_f32 v87, v94, v95
	s_waitcnt vmcnt(30)
	global_store_dwordx4 v[6:7], v[84:87], off
	v_lshl_add_u64 v[6:7], v[6:7], 0, s[10:11]
	v_lshlrev_b32_e32 v96, 16, v80
	v_and_b32_e32 v97, 0xffff0000, v80
	v_fma_f32 v88, v9, v88, v96
	v_fma_f32 v89, v9, v89, v97
	v_lshlrev_b32_e32 v96, 16, v81
	v_and_b32_e32 v97, 0xffff0000, v81
	v_fma_f32 v90, v9, v90, v96
	v_fma_f32 v91, v9, v91, v97
	v_lshlrev_b32_e32 v96, 16, v82
	v_and_b32_e32 v97, 0xffff0000, v82
	v_fma_f32 v92, v9, v92, v96
	v_fma_f32 v93, v9, v93, v97
	v_lshlrev_b32_e32 v96, 16, v83
	v_and_b32_e32 v97, 0xffff0000, v83
	v_fma_f32 v94, v9, v94, v96
	v_fma_f32 v95, v9, v95, v97
	global_load_dwordx4 v[80:83], v[4:5], off
	v_lshl_add_u64 v[4:5], v[4:5], 0, s[10:11]
	v_cvt_pk_bf16_f32 v84, v88, v89
	v_cvt_pk_bf16_f32 v85, v90, v91
	v_cvt_pk_bf16_f32 v86, v92, v93
	v_cvt_pk_bf16_f32 v87, v94, v95
	s_waitcnt vmcnt(30)
	global_store_dwordx4 v[6:7], v[84:87], off
	v_lshl_add_u64 v[6:7], v[6:7], 0, s[10:11]
	v_lshlrev_b32_e32 v96, 16, v20
	v_and_b32_e32 v97, 0xffff0000, v20
	v_fma_f32 v88, v9, v88, v96
	v_fma_f32 v89, v9, v89, v97
	v_lshlrev_b32_e32 v96, 16, v21
	v_and_b32_e32 v97, 0xffff0000, v21
	v_fma_f32 v90, v9, v90, v96
	v_fma_f32 v91, v9, v91, v97
	v_lshlrev_b32_e32 v96, 16, v22
	v_and_b32_e32 v97, 0xffff0000, v22
	v_fma_f32 v92, v9, v92, v96
	v_fma_f32 v93, v9, v93, v97
	v_lshlrev_b32_e32 v96, 16, v23
	v_and_b32_e32 v97, 0xffff0000, v23
	v_fma_f32 v94, v9, v94, v96
	v_fma_f32 v95, v9, v95, v97
	global_load_dwordx4 v[20:23], v[4:5], off
	v_lshl_add_u64 v[4:5], v[4:5], 0, s[10:11]
	v_cvt_pk_bf16_f32 v84, v88, v89
	v_cvt_pk_bf16_f32 v85, v90, v91
	v_cvt_pk_bf16_f32 v86, v92, v93
	v_cvt_pk_bf16_f32 v87, v94, v95
	s_waitcnt vmcnt(30)
	global_store_dwordx4 v[6:7], v[84:87], off
	v_lshl_add_u64 v[6:7], v[6:7], 0, s[10:11]
	v_lshlrev_b32_e32 v96, 16, v24
	v_and_b32_e32 v97, 0xffff0000, v24
	v_fma_f32 v88, v9, v88, v96
	v_fma_f32 v89, v9, v89, v97
	v_lshlrev_b32_e32 v96, 16, v25
	v_and_b32_e32 v97, 0xffff0000, v25
	v_fma_f32 v90, v9, v90, v96
	v_fma_f32 v91, v9, v91, v97
	v_lshlrev_b32_e32 v96, 16, v26
	v_and_b32_e32 v97, 0xffff0000, v26
	v_fma_f32 v92, v9, v92, v96
	v_fma_f32 v93, v9, v93, v97
	v_lshlrev_b32_e32 v96, 16, v27
	v_and_b32_e32 v97, 0xffff0000, v27
	v_fma_f32 v94, v9, v94, v96
	v_fma_f32 v95, v9, v95, v97
	global_load_dwordx4 v[24:27], v[4:5], off
	v_lshl_add_u64 v[4:5], v[4:5], 0, s[10:11]
	v_cvt_pk_bf16_f32 v84, v88, v89
	v_cvt_pk_bf16_f32 v85, v90, v91
	v_cvt_pk_bf16_f32 v86, v92, v93
	v_cvt_pk_bf16_f32 v87, v94, v95
	s_waitcnt vmcnt(30)
	global_store_dwordx4 v[6:7], v[84:87], off
	v_lshl_add_u64 v[6:7], v[6:7], 0, s[10:11]
	v_lshlrev_b32_e32 v96, 16, v28
	v_and_b32_e32 v97, 0xffff0000, v28
	v_fma_f32 v88, v9, v88, v96
	v_fma_f32 v89, v9, v89, v97
	v_lshlrev_b32_e32 v96, 16, v29
	v_and_b32_e32 v97, 0xffff0000, v29
	v_fma_f32 v90, v9, v90, v96
	v_fma_f32 v91, v9, v91, v97
	v_lshlrev_b32_e32 v96, 16, v30
	v_and_b32_e32 v97, 0xffff0000, v30
	v_fma_f32 v92, v9, v92, v96
	v_fma_f32 v93, v9, v93, v97
	v_lshlrev_b32_e32 v96, 16, v31
	v_and_b32_e32 v97, 0xffff0000, v31
	v_fma_f32 v94, v9, v94, v96
	v_fma_f32 v95, v9, v95, v97
	global_load_dwordx4 v[28:31], v[4:5], off
	v_lshl_add_u64 v[4:5], v[4:5], 0, s[10:11]
	v_cvt_pk_bf16_f32 v84, v88, v89
	v_cvt_pk_bf16_f32 v85, v90, v91
	v_cvt_pk_bf16_f32 v86, v92, v93
	v_cvt_pk_bf16_f32 v87, v94, v95
	s_waitcnt vmcnt(30)
	global_store_dwordx4 v[6:7], v[84:87], off
	v_lshl_add_u64 v[6:7], v[6:7], 0, s[10:11]
	v_lshlrev_b32_e32 v96, 16, v32
	v_and_b32_e32 v97, 0xffff0000, v32
	v_fma_f32 v88, v9, v88, v96
	v_fma_f32 v89, v9, v89, v97
	v_lshlrev_b32_e32 v96, 16, v33
	v_and_b32_e32 v97, 0xffff0000, v33
	v_fma_f32 v90, v9, v90, v96
	v_fma_f32 v91, v9, v91, v97
	v_lshlrev_b32_e32 v96, 16, v34
	v_and_b32_e32 v97, 0xffff0000, v34
	v_fma_f32 v92, v9, v92, v96
	v_fma_f32 v93, v9, v93, v97
	v_lshlrev_b32_e32 v96, 16, v35
	v_and_b32_e32 v97, 0xffff0000, v35
	v_fma_f32 v94, v9, v94, v96
	v_fma_f32 v95, v9, v95, v97
	global_load_dwordx4 v[32:35], v[4:5], off
	v_lshl_add_u64 v[4:5], v[4:5], 0, s[10:11]
	v_cvt_pk_bf16_f32 v84, v88, v89
	v_cvt_pk_bf16_f32 v85, v90, v91
	v_cvt_pk_bf16_f32 v86, v92, v93
	v_cvt_pk_bf16_f32 v87, v94, v95
	s_waitcnt vmcnt(30)
	global_store_dwordx4 v[6:7], v[84:87], off
	v_lshl_add_u64 v[6:7], v[6:7], 0, s[10:11]
	v_lshlrev_b32_e32 v96, 16, v36
	v_and_b32_e32 v97, 0xffff0000, v36
	v_fma_f32 v88, v9, v88, v96
	v_fma_f32 v89, v9, v89, v97
	v_lshlrev_b32_e32 v96, 16, v37
	v_and_b32_e32 v97, 0xffff0000, v37
	v_fma_f32 v90, v9, v90, v96
	v_fma_f32 v91, v9, v91, v97
	v_lshlrev_b32_e32 v96, 16, v38
	v_and_b32_e32 v97, 0xffff0000, v38
	v_fma_f32 v92, v9, v92, v96
	v_fma_f32 v93, v9, v93, v97
	v_lshlrev_b32_e32 v96, 16, v39
	v_and_b32_e32 v97, 0xffff0000, v39
	v_fma_f32 v94, v9, v94, v96
	v_fma_f32 v95, v9, v95, v97
	global_load_dwordx4 v[36:39], v[4:5], off
	v_lshl_add_u64 v[4:5], v[4:5], 0, s[10:11]
	v_cvt_pk_bf16_f32 v84, v88, v89
	v_cvt_pk_bf16_f32 v85, v90, v91
	v_cvt_pk_bf16_f32 v86, v92, v93
	v_cvt_pk_bf16_f32 v87, v94, v95
	s_waitcnt vmcnt(30)
	global_store_dwordx4 v[6:7], v[84:87], off
	v_lshl_add_u64 v[6:7], v[6:7], 0, s[10:11]
	v_lshlrev_b32_e32 v96, 16, v40
	v_and_b32_e32 v97, 0xffff0000, v40
	v_fma_f32 v88, v9, v88, v96
	v_fma_f32 v89, v9, v89, v97
	v_lshlrev_b32_e32 v96, 16, v41
	v_and_b32_e32 v97, 0xffff0000, v41
	v_fma_f32 v90, v9, v90, v96
	v_fma_f32 v91, v9, v91, v97
	v_lshlrev_b32_e32 v96, 16, v42
	v_and_b32_e32 v97, 0xffff0000, v42
	v_fma_f32 v92, v9, v92, v96
	v_fma_f32 v93, v9, v93, v97
	v_lshlrev_b32_e32 v96, 16, v43
	v_and_b32_e32 v97, 0xffff0000, v43
	v_fma_f32 v94, v9, v94, v96
	v_fma_f32 v95, v9, v95, v97
	global_load_dwordx4 v[40:43], v[4:5], off
	v_lshl_add_u64 v[4:5], v[4:5], 0, s[10:11]
	v_cvt_pk_bf16_f32 v84, v88, v89
	v_cvt_pk_bf16_f32 v85, v90, v91
	v_cvt_pk_bf16_f32 v86, v92, v93
	v_cvt_pk_bf16_f32 v87, v94, v95
	s_waitcnt vmcnt(30)
	global_store_dwordx4 v[6:7], v[84:87], off
	v_lshl_add_u64 v[6:7], v[6:7], 0, s[10:11]
	v_lshlrev_b32_e32 v96, 16, v44
	v_and_b32_e32 v97, 0xffff0000, v44
	v_fma_f32 v88, v9, v88, v96
	v_fma_f32 v89, v9, v89, v97
	v_lshlrev_b32_e32 v96, 16, v45
	v_and_b32_e32 v97, 0xffff0000, v45
	v_fma_f32 v90, v9, v90, v96
	v_fma_f32 v91, v9, v91, v97
	v_lshlrev_b32_e32 v96, 16, v46
	v_and_b32_e32 v97, 0xffff0000, v46
	v_fma_f32 v92, v9, v92, v96
	v_fma_f32 v93, v9, v93, v97
	v_lshlrev_b32_e32 v96, 16, v47
	v_and_b32_e32 v97, 0xffff0000, v47
	v_fma_f32 v94, v9, v94, v96
	v_fma_f32 v95, v9, v95, v97
	global_load_dwordx4 v[44:47], v[4:5], off
	v_lshl_add_u64 v[4:5], v[4:5], 0, s[10:11]
	v_cvt_pk_bf16_f32 v84, v88, v89
	v_cvt_pk_bf16_f32 v85, v90, v91
	v_cvt_pk_bf16_f32 v86, v92, v93
	v_cvt_pk_bf16_f32 v87, v94, v95
	s_waitcnt vmcnt(30)
	global_store_dwordx4 v[6:7], v[84:87], off
	v_lshl_add_u64 v[6:7], v[6:7], 0, s[10:11]
	v_lshlrev_b32_e32 v96, 16, v48
	v_and_b32_e32 v97, 0xffff0000, v48
	v_fma_f32 v88, v9, v88, v96
	v_fma_f32 v89, v9, v89, v97
	v_lshlrev_b32_e32 v96, 16, v49
	v_and_b32_e32 v97, 0xffff0000, v49
	v_fma_f32 v90, v9, v90, v96
	v_fma_f32 v91, v9, v91, v97
	v_lshlrev_b32_e32 v96, 16, v50
	v_and_b32_e32 v97, 0xffff0000, v50
	v_fma_f32 v92, v9, v92, v96
	v_fma_f32 v93, v9, v93, v97
	v_lshlrev_b32_e32 v96, 16, v51
	v_and_b32_e32 v97, 0xffff0000, v51
	v_fma_f32 v94, v9, v94, v96
	v_fma_f32 v95, v9, v95, v97
	global_load_dwordx4 v[48:51], v[4:5], off
	v_lshl_add_u64 v[4:5], v[4:5], 0, s[10:11]
	v_cvt_pk_bf16_f32 v84, v88, v89
	v_cvt_pk_bf16_f32 v85, v90, v91
	v_cvt_pk_bf16_f32 v86, v92, v93
	v_cvt_pk_bf16_f32 v87, v94, v95
	s_waitcnt vmcnt(30)
	global_store_dwordx4 v[6:7], v[84:87], off
	v_lshl_add_u64 v[6:7], v[6:7], 0, s[10:11]
	v_lshlrev_b32_e32 v96, 16, v52
	v_and_b32_e32 v97, 0xffff0000, v52
	v_fma_f32 v88, v9, v88, v96
	v_fma_f32 v89, v9, v89, v97
	v_lshlrev_b32_e32 v96, 16, v53
	v_and_b32_e32 v97, 0xffff0000, v53
	v_fma_f32 v90, v9, v90, v96
	v_fma_f32 v91, v9, v91, v97
	v_lshlrev_b32_e32 v96, 16, v54
	v_and_b32_e32 v97, 0xffff0000, v54
	v_fma_f32 v92, v9, v92, v96
	v_fma_f32 v93, v9, v93, v97
	v_lshlrev_b32_e32 v96, 16, v55
	v_and_b32_e32 v97, 0xffff0000, v55
	v_fma_f32 v94, v9, v94, v96
	v_fma_f32 v95, v9, v95, v97
	global_load_dwordx4 v[52:55], v[4:5], off
	v_lshl_add_u64 v[4:5], v[4:5], 0, s[10:11]
	v_cvt_pk_bf16_f32 v84, v88, v89
	v_cvt_pk_bf16_f32 v85, v90, v91
	v_cvt_pk_bf16_f32 v86, v92, v93
	v_cvt_pk_bf16_f32 v87, v94, v95
	s_waitcnt vmcnt(30)
	global_store_dwordx4 v[6:7], v[84:87], off
	v_lshl_add_u64 v[6:7], v[6:7], 0, s[10:11]
	v_lshlrev_b32_e32 v96, 16, v56
	v_and_b32_e32 v97, 0xffff0000, v56
	v_fma_f32 v88, v9, v88, v96
	v_fma_f32 v89, v9, v89, v97
	v_lshlrev_b32_e32 v96, 16, v57
	v_and_b32_e32 v97, 0xffff0000, v57
	v_fma_f32 v90, v9, v90, v96
	v_fma_f32 v91, v9, v91, v97
	v_lshlrev_b32_e32 v96, 16, v58
	v_and_b32_e32 v97, 0xffff0000, v58
	v_fma_f32 v92, v9, v92, v96
	v_fma_f32 v93, v9, v93, v97
	v_lshlrev_b32_e32 v96, 16, v59
	v_and_b32_e32 v97, 0xffff0000, v59
	v_fma_f32 v94, v9, v94, v96
	v_fma_f32 v95, v9, v95, v97
	global_load_dwordx4 v[56:59], v[4:5], off
	v_lshl_add_u64 v[4:5], v[4:5], 0, s[10:11]
	v_cvt_pk_bf16_f32 v84, v88, v89
	v_cvt_pk_bf16_f32 v85, v90, v91
	v_cvt_pk_bf16_f32 v86, v92, v93
	v_cvt_pk_bf16_f32 v87, v94, v95
	s_waitcnt vmcnt(30)
	global_store_dwordx4 v[6:7], v[84:87], off
	v_lshl_add_u64 v[6:7], v[6:7], 0, s[10:11]
	v_lshlrev_b32_e32 v96, 16, v60
	v_and_b32_e32 v97, 0xffff0000, v60
	v_fma_f32 v88, v9, v88, v96
	v_fma_f32 v89, v9, v89, v97
	v_lshlrev_b32_e32 v96, 16, v61
	v_and_b32_e32 v97, 0xffff0000, v61
	v_fma_f32 v90, v9, v90, v96
	v_fma_f32 v91, v9, v91, v97
	v_lshlrev_b32_e32 v96, 16, v62
	v_and_b32_e32 v97, 0xffff0000, v62
	v_fma_f32 v92, v9, v92, v96
	v_fma_f32 v93, v9, v93, v97
	v_lshlrev_b32_e32 v96, 16, v63
	v_and_b32_e32 v97, 0xffff0000, v63
	v_fma_f32 v94, v9, v94, v96
	v_fma_f32 v95, v9, v95, v97
	global_load_dwordx4 v[60:63], v[4:5], off
	v_lshl_add_u64 v[4:5], v[4:5], 0, s[10:11]
	v_cvt_pk_bf16_f32 v84, v88, v89
	v_cvt_pk_bf16_f32 v85, v90, v91
	v_cvt_pk_bf16_f32 v86, v92, v93
	v_cvt_pk_bf16_f32 v87, v94, v95
	s_waitcnt vmcnt(30)
	global_store_dwordx4 v[6:7], v[84:87], off
	v_lshl_add_u64 v[6:7], v[6:7], 0, s[10:11]
	v_lshlrev_b32_e32 v96, 16, v64
	v_and_b32_e32 v97, 0xffff0000, v64
	v_fma_f32 v88, v9, v88, v96
	v_fma_f32 v89, v9, v89, v97
	v_lshlrev_b32_e32 v96, 16, v65
	v_and_b32_e32 v97, 0xffff0000, v65
	v_fma_f32 v90, v9, v90, v96
	v_fma_f32 v91, v9, v91, v97
	v_lshlrev_b32_e32 v96, 16, v66
	v_and_b32_e32 v97, 0xffff0000, v66
	v_fma_f32 v92, v9, v92, v96
	v_fma_f32 v93, v9, v93, v97
	v_lshlrev_b32_e32 v96, 16, v67
	v_and_b32_e32 v97, 0xffff0000, v67
	v_fma_f32 v94, v9, v94, v96
	v_fma_f32 v95, v9, v95, v97
	global_load_dwordx4 v[64:67], v[4:5], off
	v_lshl_add_u64 v[4:5], v[4:5], 0, s[10:11]
	v_cvt_pk_bf16_f32 v84, v88, v89
	v_cvt_pk_bf16_f32 v85, v90, v91
	v_cvt_pk_bf16_f32 v86, v92, v93
	v_cvt_pk_bf16_f32 v87, v94, v95
	s_waitcnt vmcnt(30)
	global_store_dwordx4 v[6:7], v[84:87], off
	v_lshl_add_u64 v[6:7], v[6:7], 0, s[10:11]
	v_lshlrev_b32_e32 v96, 16, v68
	v_and_b32_e32 v97, 0xffff0000, v68
	v_fma_f32 v88, v9, v88, v96
	v_fma_f32 v89, v9, v89, v97
	v_lshlrev_b32_e32 v96, 16, v69
	v_and_b32_e32 v97, 0xffff0000, v69
	v_fma_f32 v90, v9, v90, v96
	v_fma_f32 v91, v9, v91, v97
	v_lshlrev_b32_e32 v96, 16, v70
	v_and_b32_e32 v97, 0xffff0000, v70
	v_fma_f32 v92, v9, v92, v96
	v_fma_f32 v93, v9, v93, v97
	v_lshlrev_b32_e32 v96, 16, v71
	v_and_b32_e32 v97, 0xffff0000, v71
	v_fma_f32 v94, v9, v94, v96
	v_fma_f32 v95, v9, v95, v97
	global_load_dwordx4 v[68:71], v[4:5], off
	v_lshl_add_u64 v[4:5], v[4:5], 0, s[10:11]
	v_cvt_pk_bf16_f32 v84, v88, v89
	v_cvt_pk_bf16_f32 v85, v90, v91
	v_cvt_pk_bf16_f32 v86, v92, v93
	v_cvt_pk_bf16_f32 v87, v94, v95
	s_waitcnt vmcnt(30)
	global_store_dwordx4 v[6:7], v[84:87], off
	v_lshl_add_u64 v[6:7], v[6:7], 0, s[10:11]
	v_lshlrev_b32_e32 v96, 16, v72
	v_and_b32_e32 v97, 0xffff0000, v72
	v_fma_f32 v88, v9, v88, v96
	v_fma_f32 v89, v9, v89, v97
	v_lshlrev_b32_e32 v96, 16, v73
	v_and_b32_e32 v97, 0xffff0000, v73
	v_fma_f32 v90, v9, v90, v96
	v_fma_f32 v91, v9, v91, v97
	v_lshlrev_b32_e32 v96, 16, v74
	v_and_b32_e32 v97, 0xffff0000, v74
	v_fma_f32 v92, v9, v92, v96
	v_fma_f32 v93, v9, v93, v97
	v_lshlrev_b32_e32 v96, 16, v75
	v_and_b32_e32 v97, 0xffff0000, v75
	v_fma_f32 v94, v9, v94, v96
	v_fma_f32 v95, v9, v95, v97
	global_load_dwordx4 v[72:75], v[4:5], off
	v_lshl_add_u64 v[4:5], v[4:5], 0, s[10:11]
	v_cvt_pk_bf16_f32 v84, v88, v89
	v_cvt_pk_bf16_f32 v85, v90, v91
	v_cvt_pk_bf16_f32 v86, v92, v93
	v_cvt_pk_bf16_f32 v87, v94, v95
	s_waitcnt vmcnt(30)
	global_store_dwordx4 v[6:7], v[84:87], off
	v_lshl_add_u64 v[6:7], v[6:7], 0, s[10:11]
	v_lshlrev_b32_e32 v96, 16, v76
	v_and_b32_e32 v97, 0xffff0000, v76
	v_fma_f32 v88, v9, v88, v96
	v_fma_f32 v89, v9, v89, v97
	v_lshlrev_b32_e32 v96, 16, v77
	v_and_b32_e32 v97, 0xffff0000, v77
	v_fma_f32 v90, v9, v90, v96
	v_fma_f32 v91, v9, v91, v97
	v_lshlrev_b32_e32 v96, 16, v78
	v_and_b32_e32 v97, 0xffff0000, v78
	v_fma_f32 v92, v9, v92, v96
	v_fma_f32 v93, v9, v93, v97
	v_lshlrev_b32_e32 v96, 16, v79
	v_and_b32_e32 v97, 0xffff0000, v79
	v_fma_f32 v94, v9, v94, v96
	v_fma_f32 v95, v9, v95, v97
	global_load_dwordx4 v[76:79], v[4:5], off
	v_lshl_add_u64 v[4:5], v[4:5], 0, s[10:11]
	v_cvt_pk_bf16_f32 v84, v88, v89
	v_cvt_pk_bf16_f32 v85, v90, v91
	v_cvt_pk_bf16_f32 v86, v92, v93
	v_cvt_pk_bf16_f32 v87, v94, v95
	s_waitcnt vmcnt(30)
	global_store_dwordx4 v[6:7], v[84:87], off
	v_lshl_add_u64 v[6:7], v[6:7], 0, s[10:11]
	v_lshlrev_b32_e32 v96, 16, v80
	v_and_b32_e32 v97, 0xffff0000, v80
	v_fma_f32 v88, v9, v88, v96
	v_fma_f32 v89, v9, v89, v97
	v_lshlrev_b32_e32 v96, 16, v81
	v_and_b32_e32 v97, 0xffff0000, v81
	v_fma_f32 v90, v9, v90, v96
	v_fma_f32 v91, v9, v91, v97
	v_lshlrev_b32_e32 v96, 16, v82
	v_and_b32_e32 v97, 0xffff0000, v82
	v_fma_f32 v92, v9, v92, v96
	v_fma_f32 v93, v9, v93, v97
	v_lshlrev_b32_e32 v96, 16, v83
	v_and_b32_e32 v97, 0xffff0000, v83
	v_fma_f32 v94, v9, v94, v96
	v_fma_f32 v95, v9, v95, v97
	global_load_dwordx4 v[80:83], v[4:5], off
	v_lshl_add_u64 v[4:5], v[4:5], 0, s[10:11]
	v_cvt_pk_bf16_f32 v84, v88, v89
	v_cvt_pk_bf16_f32 v85, v90, v91
	v_cvt_pk_bf16_f32 v86, v92, v93
	v_cvt_pk_bf16_f32 v87, v94, v95
	s_waitcnt vmcnt(30)
	global_store_dwordx4 v[6:7], v[84:87], off
	v_lshl_add_u64 v[6:7], v[6:7], 0, s[10:11]
	v_lshlrev_b32_e32 v96, 16, v20
	v_and_b32_e32 v97, 0xffff0000, v20
	v_fma_f32 v88, v9, v88, v96
	v_fma_f32 v89, v9, v89, v97
	v_lshlrev_b32_e32 v96, 16, v21
	v_and_b32_e32 v97, 0xffff0000, v21
	v_fma_f32 v90, v9, v90, v96
	v_fma_f32 v91, v9, v91, v97
	v_lshlrev_b32_e32 v96, 16, v22
	v_and_b32_e32 v97, 0xffff0000, v22
	v_fma_f32 v92, v9, v92, v96
	v_fma_f32 v93, v9, v93, v97
	v_lshlrev_b32_e32 v96, 16, v23
	v_and_b32_e32 v97, 0xffff0000, v23
	v_fma_f32 v94, v9, v94, v96
	v_fma_f32 v95, v9, v95, v97
	global_load_dwordx4 v[20:23], v[4:5], off
	v_lshl_add_u64 v[4:5], v[4:5], 0, s[10:11]
	v_cvt_pk_bf16_f32 v84, v88, v89
	v_cvt_pk_bf16_f32 v85, v90, v91
	v_cvt_pk_bf16_f32 v86, v92, v93
	v_cvt_pk_bf16_f32 v87, v94, v95
	s_waitcnt vmcnt(30)
	global_store_dwordx4 v[6:7], v[84:87], off
	v_lshl_add_u64 v[6:7], v[6:7], 0, s[10:11]
	v_lshlrev_b32_e32 v96, 16, v24
	v_and_b32_e32 v97, 0xffff0000, v24
	v_fma_f32 v88, v9, v88, v96
	v_fma_f32 v89, v9, v89, v97
	v_lshlrev_b32_e32 v96, 16, v25
	v_and_b32_e32 v97, 0xffff0000, v25
	v_fma_f32 v90, v9, v90, v96
	v_fma_f32 v91, v9, v91, v97
	v_lshlrev_b32_e32 v96, 16, v26
	v_and_b32_e32 v97, 0xffff0000, v26
	v_fma_f32 v92, v9, v92, v96
	v_fma_f32 v93, v9, v93, v97
	v_lshlrev_b32_e32 v96, 16, v27
	v_and_b32_e32 v97, 0xffff0000, v27
	v_fma_f32 v94, v9, v94, v96
	v_fma_f32 v95, v9, v95, v97
	global_load_dwordx4 v[24:27], v[4:5], off
	v_lshl_add_u64 v[4:5], v[4:5], 0, s[10:11]
	v_cvt_pk_bf16_f32 v84, v88, v89
	v_cvt_pk_bf16_f32 v85, v90, v91
	v_cvt_pk_bf16_f32 v86, v92, v93
	v_cvt_pk_bf16_f32 v87, v94, v95
	s_waitcnt vmcnt(30)
	global_store_dwordx4 v[6:7], v[84:87], off
	v_lshl_add_u64 v[6:7], v[6:7], 0, s[10:11]
	v_lshlrev_b32_e32 v96, 16, v28
	v_and_b32_e32 v97, 0xffff0000, v28
	v_fma_f32 v88, v9, v88, v96
	v_fma_f32 v89, v9, v89, v97
	v_lshlrev_b32_e32 v96, 16, v29
	v_and_b32_e32 v97, 0xffff0000, v29
	v_fma_f32 v90, v9, v90, v96
	v_fma_f32 v91, v9, v91, v97
	v_lshlrev_b32_e32 v96, 16, v30
	v_and_b32_e32 v97, 0xffff0000, v30
	v_fma_f32 v92, v9, v92, v96
	v_fma_f32 v93, v9, v93, v97
	v_lshlrev_b32_e32 v96, 16, v31
	v_and_b32_e32 v97, 0xffff0000, v31
	v_fma_f32 v94, v9, v94, v96
	v_fma_f32 v95, v9, v95, v97
	global_load_dwordx4 v[28:31], v[4:5], off
	v_lshl_add_u64 v[4:5], v[4:5], 0, s[10:11]
	v_cvt_pk_bf16_f32 v84, v88, v89
	v_cvt_pk_bf16_f32 v85, v90, v91
	v_cvt_pk_bf16_f32 v86, v92, v93
	v_cvt_pk_bf16_f32 v87, v94, v95
	s_waitcnt vmcnt(30)
	global_store_dwordx4 v[6:7], v[84:87], off
	v_lshl_add_u64 v[6:7], v[6:7], 0, s[10:11]
	v_lshlrev_b32_e32 v96, 16, v32
	v_and_b32_e32 v97, 0xffff0000, v32
	v_fma_f32 v88, v9, v88, v96
	v_fma_f32 v89, v9, v89, v97
	v_lshlrev_b32_e32 v96, 16, v33
	v_and_b32_e32 v97, 0xffff0000, v33
	v_fma_f32 v90, v9, v90, v96
	v_fma_f32 v91, v9, v91, v97
	v_lshlrev_b32_e32 v96, 16, v34
	v_and_b32_e32 v97, 0xffff0000, v34
	v_fma_f32 v92, v9, v92, v96
	v_fma_f32 v93, v9, v93, v97
	v_lshlrev_b32_e32 v96, 16, v35
	v_and_b32_e32 v97, 0xffff0000, v35
	v_fma_f32 v94, v9, v94, v96
	v_fma_f32 v95, v9, v95, v97
	global_load_dwordx4 v[32:35], v[4:5], off
	v_lshl_add_u64 v[4:5], v[4:5], 0, s[10:11]
	v_cvt_pk_bf16_f32 v84, v88, v89
	v_cvt_pk_bf16_f32 v85, v90, v91
	v_cvt_pk_bf16_f32 v86, v92, v93
	v_cvt_pk_bf16_f32 v87, v94, v95
	s_waitcnt vmcnt(30)
	global_store_dwordx4 v[6:7], v[84:87], off
	v_lshl_add_u64 v[6:7], v[6:7], 0, s[10:11]
	v_lshlrev_b32_e32 v96, 16, v36
	v_and_b32_e32 v97, 0xffff0000, v36
	v_fma_f32 v88, v9, v88, v96
	v_fma_f32 v89, v9, v89, v97
	v_lshlrev_b32_e32 v96, 16, v37
	v_and_b32_e32 v97, 0xffff0000, v37
	v_fma_f32 v90, v9, v90, v96
	v_fma_f32 v91, v9, v91, v97
	v_lshlrev_b32_e32 v96, 16, v38
	v_and_b32_e32 v97, 0xffff0000, v38
	v_fma_f32 v92, v9, v92, v96
	v_fma_f32 v93, v9, v93, v97
	v_lshlrev_b32_e32 v96, 16, v39
	v_and_b32_e32 v97, 0xffff0000, v39
	v_fma_f32 v94, v9, v94, v96
	v_fma_f32 v95, v9, v95, v97
	global_load_dwordx4 v[36:39], v[4:5], off
	v_lshl_add_u64 v[4:5], v[4:5], 0, s[10:11]
	v_cvt_pk_bf16_f32 v84, v88, v89
	v_cvt_pk_bf16_f32 v85, v90, v91
	v_cvt_pk_bf16_f32 v86, v92, v93
	v_cvt_pk_bf16_f32 v87, v94, v95
	s_waitcnt vmcnt(30)
	global_store_dwordx4 v[6:7], v[84:87], off
	v_lshl_add_u64 v[6:7], v[6:7], 0, s[10:11]
	v_lshlrev_b32_e32 v96, 16, v40
	v_and_b32_e32 v97, 0xffff0000, v40
	v_fma_f32 v88, v9, v88, v96
	v_fma_f32 v89, v9, v89, v97
	v_lshlrev_b32_e32 v96, 16, v41
	v_and_b32_e32 v97, 0xffff0000, v41
	v_fma_f32 v90, v9, v90, v96
	v_fma_f32 v91, v9, v91, v97
	v_lshlrev_b32_e32 v96, 16, v42
	v_and_b32_e32 v97, 0xffff0000, v42
	v_fma_f32 v92, v9, v92, v96
	v_fma_f32 v93, v9, v93, v97
	v_lshlrev_b32_e32 v96, 16, v43
	v_and_b32_e32 v97, 0xffff0000, v43
	v_fma_f32 v94, v9, v94, v96
	v_fma_f32 v95, v9, v95, v97
	global_load_dwordx4 v[40:43], v[4:5], off
	v_lshl_add_u64 v[4:5], v[4:5], 0, s[10:11]
	v_cvt_pk_bf16_f32 v84, v88, v89
	v_cvt_pk_bf16_f32 v85, v90, v91
	v_cvt_pk_bf16_f32 v86, v92, v93
	v_cvt_pk_bf16_f32 v87, v94, v95
	s_waitcnt vmcnt(30)
	global_store_dwordx4 v[6:7], v[84:87], off
	v_lshl_add_u64 v[6:7], v[6:7], 0, s[10:11]
	v_lshlrev_b32_e32 v96, 16, v44
	v_and_b32_e32 v97, 0xffff0000, v44
	v_fma_f32 v88, v9, v88, v96
	v_fma_f32 v89, v9, v89, v97
	v_lshlrev_b32_e32 v96, 16, v45
	v_and_b32_e32 v97, 0xffff0000, v45
	v_fma_f32 v90, v9, v90, v96
	v_fma_f32 v91, v9, v91, v97
	v_lshlrev_b32_e32 v96, 16, v46
	v_and_b32_e32 v97, 0xffff0000, v46
	v_fma_f32 v92, v9, v92, v96
	v_fma_f32 v93, v9, v93, v97
	v_lshlrev_b32_e32 v96, 16, v47
	v_and_b32_e32 v97, 0xffff0000, v47
	v_fma_f32 v94, v9, v94, v96
	v_fma_f32 v95, v9, v95, v97
	global_load_dwordx4 v[44:47], v[4:5], off
	v_lshl_add_u64 v[4:5], v[4:5], 0, s[10:11]
	v_cvt_pk_bf16_f32 v84, v88, v89
	v_cvt_pk_bf16_f32 v85, v90, v91
	v_cvt_pk_bf16_f32 v86, v92, v93
	v_cvt_pk_bf16_f32 v87, v94, v95
	s_waitcnt vmcnt(30)
	global_store_dwordx4 v[6:7], v[84:87], off
	v_lshl_add_u64 v[6:7], v[6:7], 0, s[10:11]
	v_lshlrev_b32_e32 v96, 16, v48
	v_and_b32_e32 v97, 0xffff0000, v48
	v_fma_f32 v88, v9, v88, v96
	v_fma_f32 v89, v9, v89, v97
	v_lshlrev_b32_e32 v96, 16, v49
	v_and_b32_e32 v97, 0xffff0000, v49
	v_fma_f32 v90, v9, v90, v96
	v_fma_f32 v91, v9, v91, v97
	v_lshlrev_b32_e32 v96, 16, v50
	v_and_b32_e32 v97, 0xffff0000, v50
	v_fma_f32 v92, v9, v92, v96
	v_fma_f32 v93, v9, v93, v97
	v_lshlrev_b32_e32 v96, 16, v51
	v_and_b32_e32 v97, 0xffff0000, v51
	v_fma_f32 v94, v9, v94, v96
	v_fma_f32 v95, v9, v95, v97
	global_load_dwordx4 v[48:51], v[4:5], off
	v_lshl_add_u64 v[4:5], v[4:5], 0, s[10:11]
	v_cvt_pk_bf16_f32 v84, v88, v89
	v_cvt_pk_bf16_f32 v85, v90, v91
	v_cvt_pk_bf16_f32 v86, v92, v93
	v_cvt_pk_bf16_f32 v87, v94, v95
	s_waitcnt vmcnt(30)
	global_store_dwordx4 v[6:7], v[84:87], off
	v_lshl_add_u64 v[6:7], v[6:7], 0, s[10:11]
	v_lshlrev_b32_e32 v96, 16, v52
	v_and_b32_e32 v97, 0xffff0000, v52
	v_fma_f32 v88, v9, v88, v96
	v_fma_f32 v89, v9, v89, v97
	v_lshlrev_b32_e32 v96, 16, v53
	v_and_b32_e32 v97, 0xffff0000, v53
	v_fma_f32 v90, v9, v90, v96
	v_fma_f32 v91, v9, v91, v97
	v_lshlrev_b32_e32 v96, 16, v54
	v_and_b32_e32 v97, 0xffff0000, v54
	v_fma_f32 v92, v9, v92, v96
	v_fma_f32 v93, v9, v93, v97
	v_lshlrev_b32_e32 v96, 16, v55
	v_and_b32_e32 v97, 0xffff0000, v55
	v_fma_f32 v94, v9, v94, v96
	v_fma_f32 v95, v9, v95, v97
	global_load_dwordx4 v[52:55], v[4:5], off
	v_lshl_add_u64 v[4:5], v[4:5], 0, s[10:11]
	v_cvt_pk_bf16_f32 v84, v88, v89
	v_cvt_pk_bf16_f32 v85, v90, v91
	v_cvt_pk_bf16_f32 v86, v92, v93
	v_cvt_pk_bf16_f32 v87, v94, v95
	s_waitcnt vmcnt(30)
	global_store_dwordx4 v[6:7], v[84:87], off
	v_lshl_add_u64 v[6:7], v[6:7], 0, s[10:11]
	v_lshlrev_b32_e32 v96, 16, v56
	v_and_b32_e32 v97, 0xffff0000, v56
	v_fma_f32 v88, v9, v88, v96
	v_fma_f32 v89, v9, v89, v97
	v_lshlrev_b32_e32 v96, 16, v57
	v_and_b32_e32 v97, 0xffff0000, v57
	v_fma_f32 v90, v9, v90, v96
	v_fma_f32 v91, v9, v91, v97
	v_lshlrev_b32_e32 v96, 16, v58
	v_and_b32_e32 v97, 0xffff0000, v58
	v_fma_f32 v92, v9, v92, v96
	v_fma_f32 v93, v9, v93, v97
	v_lshlrev_b32_e32 v96, 16, v59
	v_and_b32_e32 v97, 0xffff0000, v59
	v_fma_f32 v94, v9, v94, v96
	v_fma_f32 v95, v9, v95, v97
	global_load_dwordx4 v[56:59], v[4:5], off
	v_lshl_add_u64 v[4:5], v[4:5], 0, s[10:11]
	v_cvt_pk_bf16_f32 v84, v88, v89
	v_cvt_pk_bf16_f32 v85, v90, v91
	v_cvt_pk_bf16_f32 v86, v92, v93
	v_cvt_pk_bf16_f32 v87, v94, v95
	s_waitcnt vmcnt(30)
	global_store_dwordx4 v[6:7], v[84:87], off
	v_lshl_add_u64 v[6:7], v[6:7], 0, s[10:11]
	v_lshlrev_b32_e32 v96, 16, v60
	v_and_b32_e32 v97, 0xffff0000, v60
	v_fma_f32 v88, v9, v88, v96
	v_fma_f32 v89, v9, v89, v97
	v_lshlrev_b32_e32 v96, 16, v61
	v_and_b32_e32 v97, 0xffff0000, v61
	v_fma_f32 v90, v9, v90, v96
	v_fma_f32 v91, v9, v91, v97
	v_lshlrev_b32_e32 v96, 16, v62
	v_and_b32_e32 v97, 0xffff0000, v62
	v_fma_f32 v92, v9, v92, v96
	v_fma_f32 v93, v9, v93, v97
	v_lshlrev_b32_e32 v96, 16, v63
	v_and_b32_e32 v97, 0xffff0000, v63
	v_fma_f32 v94, v9, v94, v96
	v_fma_f32 v95, v9, v95, v97
	global_load_dwordx4 v[60:63], v[4:5], off
	v_lshl_add_u64 v[4:5], v[4:5], 0, s[10:11]
	v_cvt_pk_bf16_f32 v84, v88, v89
	v_cvt_pk_bf16_f32 v85, v90, v91
	v_cvt_pk_bf16_f32 v86, v92, v93
	v_cvt_pk_bf16_f32 v87, v94, v95
	s_waitcnt vmcnt(30)
	global_store_dwordx4 v[6:7], v[84:87], off
	v_lshl_add_u64 v[6:7], v[6:7], 0, s[10:11]
	v_lshlrev_b32_e32 v96, 16, v64
	v_and_b32_e32 v97, 0xffff0000, v64
	v_fma_f32 v88, v9, v88, v96
	v_fma_f32 v89, v9, v89, v97
	v_lshlrev_b32_e32 v96, 16, v65
	v_and_b32_e32 v97, 0xffff0000, v65
	v_fma_f32 v90, v9, v90, v96
	v_fma_f32 v91, v9, v91, v97
	v_lshlrev_b32_e32 v96, 16, v66
	v_and_b32_e32 v97, 0xffff0000, v66
	v_fma_f32 v92, v9, v92, v96
	v_fma_f32 v93, v9, v93, v97
	v_lshlrev_b32_e32 v96, 16, v67
	v_and_b32_e32 v97, 0xffff0000, v67
	v_fma_f32 v94, v9, v94, v96
	v_fma_f32 v95, v9, v95, v97
	global_load_dwordx4 v[64:67], v[4:5], off
	v_lshl_add_u64 v[4:5], v[4:5], 0, s[10:11]
	v_cvt_pk_bf16_f32 v84, v88, v89
	v_cvt_pk_bf16_f32 v85, v90, v91
	v_cvt_pk_bf16_f32 v86, v92, v93
	v_cvt_pk_bf16_f32 v87, v94, v95
	s_waitcnt vmcnt(30)
	global_store_dwordx4 v[6:7], v[84:87], off
	v_lshl_add_u64 v[6:7], v[6:7], 0, s[10:11]
	v_lshlrev_b32_e32 v96, 16, v68
	v_and_b32_e32 v97, 0xffff0000, v68
	v_fma_f32 v88, v9, v88, v96
	v_fma_f32 v89, v9, v89, v97
	v_lshlrev_b32_e32 v96, 16, v69
	v_and_b32_e32 v97, 0xffff0000, v69
	v_fma_f32 v90, v9, v90, v96
	v_fma_f32 v91, v9, v91, v97
	v_lshlrev_b32_e32 v96, 16, v70
	v_and_b32_e32 v97, 0xffff0000, v70
	v_fma_f32 v92, v9, v92, v96
	v_fma_f32 v93, v9, v93, v97
	v_lshlrev_b32_e32 v96, 16, v71
	v_and_b32_e32 v97, 0xffff0000, v71
	v_fma_f32 v94, v9, v94, v96
	v_fma_f32 v95, v9, v95, v97
	global_load_dwordx4 v[68:71], v[4:5], off
	v_lshl_add_u64 v[4:5], v[4:5], 0, s[10:11]
	v_cvt_pk_bf16_f32 v84, v88, v89
	v_cvt_pk_bf16_f32 v85, v90, v91
	v_cvt_pk_bf16_f32 v86, v92, v93
	v_cvt_pk_bf16_f32 v87, v94, v95
	s_waitcnt vmcnt(30)
	global_store_dwordx4 v[6:7], v[84:87], off
	v_lshl_add_u64 v[6:7], v[6:7], 0, s[10:11]
	v_lshlrev_b32_e32 v96, 16, v72
	v_and_b32_e32 v97, 0xffff0000, v72
	v_fma_f32 v88, v9, v88, v96
	v_fma_f32 v89, v9, v89, v97
	v_lshlrev_b32_e32 v96, 16, v73
	v_and_b32_e32 v97, 0xffff0000, v73
	v_fma_f32 v90, v9, v90, v96
	v_fma_f32 v91, v9, v91, v97
	v_lshlrev_b32_e32 v96, 16, v74
	v_and_b32_e32 v97, 0xffff0000, v74
	v_fma_f32 v92, v9, v92, v96
	v_fma_f32 v93, v9, v93, v97
	v_lshlrev_b32_e32 v96, 16, v75
	v_and_b32_e32 v97, 0xffff0000, v75
	v_fma_f32 v94, v9, v94, v96
	v_fma_f32 v95, v9, v95, v97
	global_load_dwordx4 v[72:75], v[4:5], off
	v_lshl_add_u64 v[4:5], v[4:5], 0, s[10:11]
	v_cvt_pk_bf16_f32 v84, v88, v89
	v_cvt_pk_bf16_f32 v85, v90, v91
	v_cvt_pk_bf16_f32 v86, v92, v93
	v_cvt_pk_bf16_f32 v87, v94, v95
	s_waitcnt vmcnt(30)
	global_store_dwordx4 v[6:7], v[84:87], off
	v_lshl_add_u64 v[6:7], v[6:7], 0, s[10:11]
	v_lshlrev_b32_e32 v96, 16, v76
	v_and_b32_e32 v97, 0xffff0000, v76
	v_fma_f32 v88, v9, v88, v96
	v_fma_f32 v89, v9, v89, v97
	v_lshlrev_b32_e32 v96, 16, v77
	v_and_b32_e32 v97, 0xffff0000, v77
	v_fma_f32 v90, v9, v90, v96
	v_fma_f32 v91, v9, v91, v97
	v_lshlrev_b32_e32 v96, 16, v78
	v_and_b32_e32 v97, 0xffff0000, v78
	v_fma_f32 v92, v9, v92, v96
	v_fma_f32 v93, v9, v93, v97
	v_lshlrev_b32_e32 v96, 16, v79
	v_and_b32_e32 v97, 0xffff0000, v79
	v_fma_f32 v94, v9, v94, v96
	v_fma_f32 v95, v9, v95, v97
	global_load_dwordx4 v[76:79], v[4:5], off
	v_lshl_add_u64 v[4:5], v[4:5], 0, s[10:11]
	v_cvt_pk_bf16_f32 v84, v88, v89
	v_cvt_pk_bf16_f32 v85, v90, v91
	v_cvt_pk_bf16_f32 v86, v92, v93
	v_cvt_pk_bf16_f32 v87, v94, v95
	s_waitcnt vmcnt(30)
	global_store_dwordx4 v[6:7], v[84:87], off
	v_lshl_add_u64 v[6:7], v[6:7], 0, s[10:11]
	v_lshlrev_b32_e32 v96, 16, v80
	v_and_b32_e32 v97, 0xffff0000, v80
	v_fma_f32 v88, v9, v88, v96
	v_fma_f32 v89, v9, v89, v97
	v_lshlrev_b32_e32 v96, 16, v81
	v_and_b32_e32 v97, 0xffff0000, v81
	v_fma_f32 v90, v9, v90, v96
	v_fma_f32 v91, v9, v91, v97
	v_lshlrev_b32_e32 v96, 16, v82
	v_and_b32_e32 v97, 0xffff0000, v82
	v_fma_f32 v92, v9, v92, v96
	v_fma_f32 v93, v9, v93, v97
	v_lshlrev_b32_e32 v96, 16, v83
	v_and_b32_e32 v97, 0xffff0000, v83
	v_fma_f32 v94, v9, v94, v96
	v_fma_f32 v95, v9, v95, v97
	global_load_dwordx4 v[80:83], v[4:5], off
	v_lshl_add_u64 v[4:5], v[4:5], 0, s[10:11]
	v_cvt_pk_bf16_f32 v84, v88, v89
	v_cvt_pk_bf16_f32 v85, v90, v91
	v_cvt_pk_bf16_f32 v86, v92, v93
	v_cvt_pk_bf16_f32 v87, v94, v95
	s_waitcnt vmcnt(30)
	global_store_dwordx4 v[6:7], v[84:87], off
	v_lshl_add_u64 v[6:7], v[6:7], 0, s[10:11]
	v_lshlrev_b32_e32 v96, 16, v20
	v_and_b32_e32 v97, 0xffff0000, v20
	v_fma_f32 v88, v9, v88, v96
	v_fma_f32 v89, v9, v89, v97
	v_lshlrev_b32_e32 v96, 16, v21
	v_and_b32_e32 v97, 0xffff0000, v21
	v_fma_f32 v90, v9, v90, v96
	v_fma_f32 v91, v9, v91, v97
	v_lshlrev_b32_e32 v96, 16, v22
	v_and_b32_e32 v97, 0xffff0000, v22
	v_fma_f32 v92, v9, v92, v96
	v_fma_f32 v93, v9, v93, v97
	v_lshlrev_b32_e32 v96, 16, v23
	v_and_b32_e32 v97, 0xffff0000, v23
	v_fma_f32 v94, v9, v94, v96
	v_fma_f32 v95, v9, v95, v97
	v_cvt_pk_bf16_f32 v84, v88, v89
	v_cvt_pk_bf16_f32 v85, v90, v91
	v_cvt_pk_bf16_f32 v86, v92, v93
	v_cvt_pk_bf16_f32 v87, v94, v95
	s_waitcnt vmcnt(29)
	global_store_dwordx4 v[6:7], v[84:87], off
	v_lshl_add_u64 v[6:7], v[6:7], 0, s[10:11]
	v_lshlrev_b32_e32 v96, 16, v24
	v_and_b32_e32 v97, 0xffff0000, v24
	v_fma_f32 v88, v9, v88, v96
	v_fma_f32 v89, v9, v89, v97
	v_lshlrev_b32_e32 v96, 16, v25
	v_and_b32_e32 v97, 0xffff0000, v25
	v_fma_f32 v90, v9, v90, v96
	v_fma_f32 v91, v9, v91, v97
	v_lshlrev_b32_e32 v96, 16, v26
	v_and_b32_e32 v97, 0xffff0000, v26
	v_fma_f32 v92, v9, v92, v96
	v_fma_f32 v93, v9, v93, v97
	v_lshlrev_b32_e32 v96, 16, v27
	v_and_b32_e32 v97, 0xffff0000, v27
	v_fma_f32 v94, v9, v94, v96
	v_fma_f32 v95, v9, v95, v97
	v_cvt_pk_bf16_f32 v84, v88, v89
	v_cvt_pk_bf16_f32 v85, v90, v91
	v_cvt_pk_bf16_f32 v86, v92, v93
	v_cvt_pk_bf16_f32 v87, v94, v95
	s_waitcnt vmcnt(28)
	global_store_dwordx4 v[6:7], v[84:87], off
	v_lshl_add_u64 v[6:7], v[6:7], 0, s[10:11]
	v_lshlrev_b32_e32 v96, 16, v28
	v_and_b32_e32 v97, 0xffff0000, v28
	v_fma_f32 v88, v9, v88, v96
	v_fma_f32 v89, v9, v89, v97
	v_lshlrev_b32_e32 v96, 16, v29
	v_and_b32_e32 v97, 0xffff0000, v29
	v_fma_f32 v90, v9, v90, v96
	v_fma_f32 v91, v9, v91, v97
	v_lshlrev_b32_e32 v96, 16, v30
	v_and_b32_e32 v97, 0xffff0000, v30
	v_fma_f32 v92, v9, v92, v96
	v_fma_f32 v93, v9, v93, v97
	v_lshlrev_b32_e32 v96, 16, v31
	v_and_b32_e32 v97, 0xffff0000, v31
	v_fma_f32 v94, v9, v94, v96
	v_fma_f32 v95, v9, v95, v97
	v_cvt_pk_bf16_f32 v84, v88, v89
	v_cvt_pk_bf16_f32 v85, v90, v91
	v_cvt_pk_bf16_f32 v86, v92, v93
	v_cvt_pk_bf16_f32 v87, v94, v95
	s_waitcnt vmcnt(27)
	global_store_dwordx4 v[6:7], v[84:87], off
	v_lshl_add_u64 v[6:7], v[6:7], 0, s[10:11]
	v_lshlrev_b32_e32 v96, 16, v32
	v_and_b32_e32 v97, 0xffff0000, v32
	v_fma_f32 v88, v9, v88, v96
	v_fma_f32 v89, v9, v89, v97
	v_lshlrev_b32_e32 v96, 16, v33
	v_and_b32_e32 v97, 0xffff0000, v33
	v_fma_f32 v90, v9, v90, v96
	v_fma_f32 v91, v9, v91, v97
	v_lshlrev_b32_e32 v96, 16, v34
	v_and_b32_e32 v97, 0xffff0000, v34
	v_fma_f32 v92, v9, v92, v96
	v_fma_f32 v93, v9, v93, v97
	v_lshlrev_b32_e32 v96, 16, v35
	v_and_b32_e32 v97, 0xffff0000, v35
	v_fma_f32 v94, v9, v94, v96
	v_fma_f32 v95, v9, v95, v97
	v_cvt_pk_bf16_f32 v84, v88, v89
	v_cvt_pk_bf16_f32 v85, v90, v91
	v_cvt_pk_bf16_f32 v86, v92, v93
	v_cvt_pk_bf16_f32 v87, v94, v95
	s_waitcnt vmcnt(26)
	global_store_dwordx4 v[6:7], v[84:87], off
	v_lshl_add_u64 v[6:7], v[6:7], 0, s[10:11]
	v_lshlrev_b32_e32 v96, 16, v36
	v_and_b32_e32 v97, 0xffff0000, v36
	v_fma_f32 v88, v9, v88, v96
	v_fma_f32 v89, v9, v89, v97
	v_lshlrev_b32_e32 v96, 16, v37
	v_and_b32_e32 v97, 0xffff0000, v37
	v_fma_f32 v90, v9, v90, v96
	v_fma_f32 v91, v9, v91, v97
	v_lshlrev_b32_e32 v96, 16, v38
	v_and_b32_e32 v97, 0xffff0000, v38
	v_fma_f32 v92, v9, v92, v96
	v_fma_f32 v93, v9, v93, v97
	v_lshlrev_b32_e32 v96, 16, v39
	v_and_b32_e32 v97, 0xffff0000, v39
	v_fma_f32 v94, v9, v94, v96
	v_fma_f32 v95, v9, v95, v97
	v_cvt_pk_bf16_f32 v84, v88, v89
	v_cvt_pk_bf16_f32 v85, v90, v91
	v_cvt_pk_bf16_f32 v86, v92, v93
	v_cvt_pk_bf16_f32 v87, v94, v95
	s_waitcnt vmcnt(25)
	global_store_dwordx4 v[6:7], v[84:87], off
	v_lshl_add_u64 v[6:7], v[6:7], 0, s[10:11]
	v_lshlrev_b32_e32 v96, 16, v40
	v_and_b32_e32 v97, 0xffff0000, v40
	v_fma_f32 v88, v9, v88, v96
	v_fma_f32 v89, v9, v89, v97
	v_lshlrev_b32_e32 v96, 16, v41
	v_and_b32_e32 v97, 0xffff0000, v41
	v_fma_f32 v90, v9, v90, v96
	v_fma_f32 v91, v9, v91, v97
	v_lshlrev_b32_e32 v96, 16, v42
	v_and_b32_e32 v97, 0xffff0000, v42
	v_fma_f32 v92, v9, v92, v96
	v_fma_f32 v93, v9, v93, v97
	v_lshlrev_b32_e32 v96, 16, v43
	v_and_b32_e32 v97, 0xffff0000, v43
	v_fma_f32 v94, v9, v94, v96
	v_fma_f32 v95, v9, v95, v97
	v_cvt_pk_bf16_f32 v84, v88, v89
	v_cvt_pk_bf16_f32 v85, v90, v91
	v_cvt_pk_bf16_f32 v86, v92, v93
	v_cvt_pk_bf16_f32 v87, v94, v95
	s_waitcnt vmcnt(24)
	global_store_dwordx4 v[6:7], v[84:87], off
	v_lshl_add_u64 v[6:7], v[6:7], 0, s[10:11]
	v_lshlrev_b32_e32 v96, 16, v44
	v_and_b32_e32 v97, 0xffff0000, v44
	v_fma_f32 v88, v9, v88, v96
	v_fma_f32 v89, v9, v89, v97
	v_lshlrev_b32_e32 v96, 16, v45
	v_and_b32_e32 v97, 0xffff0000, v45
	v_fma_f32 v90, v9, v90, v96
	v_fma_f32 v91, v9, v91, v97
	v_lshlrev_b32_e32 v96, 16, v46
	v_and_b32_e32 v97, 0xffff0000, v46
	v_fma_f32 v92, v9, v92, v96
	v_fma_f32 v93, v9, v93, v97
	v_lshlrev_b32_e32 v96, 16, v47
	v_and_b32_e32 v97, 0xffff0000, v47
	v_fma_f32 v94, v9, v94, v96
	v_fma_f32 v95, v9, v95, v97
	v_cvt_pk_bf16_f32 v84, v88, v89
	v_cvt_pk_bf16_f32 v85, v90, v91
	v_cvt_pk_bf16_f32 v86, v92, v93
	v_cvt_pk_bf16_f32 v87, v94, v95
	s_waitcnt vmcnt(23)
	global_store_dwordx4 v[6:7], v[84:87], off
	v_lshl_add_u64 v[6:7], v[6:7], 0, s[10:11]
	v_lshlrev_b32_e32 v96, 16, v48
	v_and_b32_e32 v97, 0xffff0000, v48
	v_fma_f32 v88, v9, v88, v96
	v_fma_f32 v89, v9, v89, v97
	v_lshlrev_b32_e32 v96, 16, v49
	v_and_b32_e32 v97, 0xffff0000, v49
	v_fma_f32 v90, v9, v90, v96
	v_fma_f32 v91, v9, v91, v97
	v_lshlrev_b32_e32 v96, 16, v50
	v_and_b32_e32 v97, 0xffff0000, v50
	v_fma_f32 v92, v9, v92, v96
	v_fma_f32 v93, v9, v93, v97
	v_lshlrev_b32_e32 v96, 16, v51
	v_and_b32_e32 v97, 0xffff0000, v51
	v_fma_f32 v94, v9, v94, v96
	v_fma_f32 v95, v9, v95, v97
	v_cvt_pk_bf16_f32 v84, v88, v89
	v_cvt_pk_bf16_f32 v85, v90, v91
	v_cvt_pk_bf16_f32 v86, v92, v93
	v_cvt_pk_bf16_f32 v87, v94, v95
	s_waitcnt vmcnt(22)
	global_store_dwordx4 v[6:7], v[84:87], off
	v_lshl_add_u64 v[6:7], v[6:7], 0, s[10:11]
	v_lshlrev_b32_e32 v96, 16, v52
	v_and_b32_e32 v97, 0xffff0000, v52
	v_fma_f32 v88, v9, v88, v96
	v_fma_f32 v89, v9, v89, v97
	v_lshlrev_b32_e32 v96, 16, v53
	v_and_b32_e32 v97, 0xffff0000, v53
	v_fma_f32 v90, v9, v90, v96
	v_fma_f32 v91, v9, v91, v97
	v_lshlrev_b32_e32 v96, 16, v54
	v_and_b32_e32 v97, 0xffff0000, v54
	v_fma_f32 v92, v9, v92, v96
	v_fma_f32 v93, v9, v93, v97
	v_lshlrev_b32_e32 v96, 16, v55
	v_and_b32_e32 v97, 0xffff0000, v55
	v_fma_f32 v94, v9, v94, v96
	v_fma_f32 v95, v9, v95, v97
	v_cvt_pk_bf16_f32 v84, v88, v89
	v_cvt_pk_bf16_f32 v85, v90, v91
	v_cvt_pk_bf16_f32 v86, v92, v93
	v_cvt_pk_bf16_f32 v87, v94, v95
	s_waitcnt vmcnt(21)
	global_store_dwordx4 v[6:7], v[84:87], off
	v_lshl_add_u64 v[6:7], v[6:7], 0, s[10:11]
	v_lshlrev_b32_e32 v96, 16, v56
	v_and_b32_e32 v97, 0xffff0000, v56
	v_fma_f32 v88, v9, v88, v96
	v_fma_f32 v89, v9, v89, v97
	v_lshlrev_b32_e32 v96, 16, v57
	v_and_b32_e32 v97, 0xffff0000, v57
	v_fma_f32 v90, v9, v90, v96
	v_fma_f32 v91, v9, v91, v97
	v_lshlrev_b32_e32 v96, 16, v58
	v_and_b32_e32 v97, 0xffff0000, v58
	v_fma_f32 v92, v9, v92, v96
	v_fma_f32 v93, v9, v93, v97
	v_lshlrev_b32_e32 v96, 16, v59
	v_and_b32_e32 v97, 0xffff0000, v59
	v_fma_f32 v94, v9, v94, v96
	v_fma_f32 v95, v9, v95, v97
	v_cvt_pk_bf16_f32 v84, v88, v89
	v_cvt_pk_bf16_f32 v85, v90, v91
	v_cvt_pk_bf16_f32 v86, v92, v93
	v_cvt_pk_bf16_f32 v87, v94, v95
	s_waitcnt vmcnt(20)
	global_store_dwordx4 v[6:7], v[84:87], off
	v_lshl_add_u64 v[6:7], v[6:7], 0, s[10:11]
	v_lshlrev_b32_e32 v96, 16, v60
	v_and_b32_e32 v97, 0xffff0000, v60
	v_fma_f32 v88, v9, v88, v96
	v_fma_f32 v89, v9, v89, v97
	v_lshlrev_b32_e32 v96, 16, v61
	v_and_b32_e32 v97, 0xffff0000, v61
	v_fma_f32 v90, v9, v90, v96
	v_fma_f32 v91, v9, v91, v97
	v_lshlrev_b32_e32 v96, 16, v62
	v_and_b32_e32 v97, 0xffff0000, v62
	v_fma_f32 v92, v9, v92, v96
	v_fma_f32 v93, v9, v93, v97
	v_lshlrev_b32_e32 v96, 16, v63
	v_and_b32_e32 v97, 0xffff0000, v63
	v_fma_f32 v94, v9, v94, v96
	v_fma_f32 v95, v9, v95, v97
	v_cvt_pk_bf16_f32 v84, v88, v89
	v_cvt_pk_bf16_f32 v85, v90, v91
	v_cvt_pk_bf16_f32 v86, v92, v93
	v_cvt_pk_bf16_f32 v87, v94, v95
	s_waitcnt vmcnt(19)
	global_store_dwordx4 v[6:7], v[84:87], off
	v_lshl_add_u64 v[6:7], v[6:7], 0, s[10:11]
	v_lshlrev_b32_e32 v96, 16, v64
	v_and_b32_e32 v97, 0xffff0000, v64
	v_fma_f32 v88, v9, v88, v96
	v_fma_f32 v89, v9, v89, v97
	v_lshlrev_b32_e32 v96, 16, v65
	v_and_b32_e32 v97, 0xffff0000, v65
	v_fma_f32 v90, v9, v90, v96
	v_fma_f32 v91, v9, v91, v97
	v_lshlrev_b32_e32 v96, 16, v66
	v_and_b32_e32 v97, 0xffff0000, v66
	v_fma_f32 v92, v9, v92, v96
	v_fma_f32 v93, v9, v93, v97
	v_lshlrev_b32_e32 v96, 16, v67
	v_and_b32_e32 v97, 0xffff0000, v67
	v_fma_f32 v94, v9, v94, v96
	v_fma_f32 v95, v9, v95, v97
	v_cvt_pk_bf16_f32 v84, v88, v89
	v_cvt_pk_bf16_f32 v85, v90, v91
	v_cvt_pk_bf16_f32 v86, v92, v93
	v_cvt_pk_bf16_f32 v87, v94, v95
	s_waitcnt vmcnt(18)
	global_store_dwordx4 v[6:7], v[84:87], off
	v_lshl_add_u64 v[6:7], v[6:7], 0, s[10:11]
	v_lshlrev_b32_e32 v96, 16, v68
	v_and_b32_e32 v97, 0xffff0000, v68
	v_fma_f32 v88, v9, v88, v96
	v_fma_f32 v89, v9, v89, v97
	v_lshlrev_b32_e32 v96, 16, v69
	v_and_b32_e32 v97, 0xffff0000, v69
	v_fma_f32 v90, v9, v90, v96
	v_fma_f32 v91, v9, v91, v97
	v_lshlrev_b32_e32 v96, 16, v70
	v_and_b32_e32 v97, 0xffff0000, v70
	v_fma_f32 v92, v9, v92, v96
	v_fma_f32 v93, v9, v93, v97
	v_lshlrev_b32_e32 v96, 16, v71
	v_and_b32_e32 v97, 0xffff0000, v71
	v_fma_f32 v94, v9, v94, v96
	v_fma_f32 v95, v9, v95, v97
	v_cvt_pk_bf16_f32 v84, v88, v89
	v_cvt_pk_bf16_f32 v85, v90, v91
	v_cvt_pk_bf16_f32 v86, v92, v93
	v_cvt_pk_bf16_f32 v87, v94, v95
	s_waitcnt vmcnt(17)
	global_store_dwordx4 v[6:7], v[84:87], off
	v_lshl_add_u64 v[6:7], v[6:7], 0, s[10:11]
	v_lshlrev_b32_e32 v96, 16, v72
	v_and_b32_e32 v97, 0xffff0000, v72
	v_fma_f32 v88, v9, v88, v96
	v_fma_f32 v89, v9, v89, v97
	v_lshlrev_b32_e32 v96, 16, v73
	v_and_b32_e32 v97, 0xffff0000, v73
	v_fma_f32 v90, v9, v90, v96
	v_fma_f32 v91, v9, v91, v97
	v_lshlrev_b32_e32 v96, 16, v74
	v_and_b32_e32 v97, 0xffff0000, v74
	v_fma_f32 v92, v9, v92, v96
	v_fma_f32 v93, v9, v93, v97
	v_lshlrev_b32_e32 v96, 16, v75
	v_and_b32_e32 v97, 0xffff0000, v75
	v_fma_f32 v94, v9, v94, v96
	v_fma_f32 v95, v9, v95, v97
	v_cvt_pk_bf16_f32 v84, v88, v89
	v_cvt_pk_bf16_f32 v85, v90, v91
	v_cvt_pk_bf16_f32 v86, v92, v93
	v_cvt_pk_bf16_f32 v87, v94, v95
	s_waitcnt vmcnt(16)
	global_store_dwordx4 v[6:7], v[84:87], off
	v_lshl_add_u64 v[6:7], v[6:7], 0, s[10:11]
	v_lshlrev_b32_e32 v96, 16, v76
	v_and_b32_e32 v97, 0xffff0000, v76
	v_fma_f32 v88, v9, v88, v96
	v_fma_f32 v89, v9, v89, v97
	v_lshlrev_b32_e32 v96, 16, v77
	v_and_b32_e32 v97, 0xffff0000, v77
	v_fma_f32 v90, v9, v90, v96
	v_fma_f32 v91, v9, v91, v97
	v_lshlrev_b32_e32 v96, 16, v78
	v_and_b32_e32 v97, 0xffff0000, v78
	v_fma_f32 v92, v9, v92, v96
	v_fma_f32 v93, v9, v93, v97
	v_lshlrev_b32_e32 v96, 16, v79
	v_and_b32_e32 v97, 0xffff0000, v79
	v_fma_f32 v94, v9, v94, v96
	v_fma_f32 v95, v9, v95, v97
	v_cvt_pk_bf16_f32 v84, v88, v89
	v_cvt_pk_bf16_f32 v85, v90, v91
	v_cvt_pk_bf16_f32 v86, v92, v93
	v_cvt_pk_bf16_f32 v87, v94, v95
	s_waitcnt vmcnt(15)
	global_store_dwordx4 v[6:7], v[84:87], off
	v_lshl_add_u64 v[6:7], v[6:7], 0, s[10:11]
	v_lshlrev_b32_e32 v96, 16, v80
	v_and_b32_e32 v97, 0xffff0000, v80
	v_fma_f32 v88, v9, v88, v96
	v_fma_f32 v89, v9, v89, v97
	v_lshlrev_b32_e32 v96, 16, v81
	v_and_b32_e32 v97, 0xffff0000, v81
	v_fma_f32 v90, v9, v90, v96
	v_fma_f32 v91, v9, v91, v97
	v_lshlrev_b32_e32 v96, 16, v82
	v_and_b32_e32 v97, 0xffff0000, v82
	v_fma_f32 v92, v9, v92, v96
	v_fma_f32 v93, v9, v93, v97
	v_lshlrev_b32_e32 v96, 16, v83
	v_and_b32_e32 v97, 0xffff0000, v83
	v_fma_f32 v94, v9, v94, v96
	v_fma_f32 v95, v9, v95, v97
	v_add_u32_e32 v0, s38, v0
	v_cmp_lt_i32_e32 vcc, s66, v0
	s_or_b64 s[6:7], vcc, s[6:7]
	v_add_u16_e32 v8, s38, v8
	s_andn2_b64 exec, exec, s[6:7]
	s_cbranch_execnz .LBB0_431
